# P10 final output stores marked non-temporal (streaming; the output is never re-read)
# baseline (speedup 1.0000x reference)
; DI float frsq(float x) { return __builtin_amdgcn_rsqf(x); }
; DI void norm_row_bf16_to_f32(const bf16_t* xrow, const float* g, float* orow, int lane) {
;     u32x4 v[4]; float s = 0.f;
; #pragma unroll
;     for (int j = 0; j < 4; ++j) {
;         v[j] = *((const u32x4*)xrow + lane + 64 * j);
;         float f;
;         f = bflo(v[j].x); s += f * f; f = bfhi(v[j].x); s += f * f; f = bflo(v[j].y); s += f * f; f = bfhi(v[j].y); s += f * f;
;         f = bflo(v[j].z); s += f * f; f = bfhi(v[j].z); s += f * f; f = bflo(v[j].w); s += f * f; f = bfhi(v[j].w); s += f * f;
;     }
;     s = wave_sum(s);
;     const float rs = frsq(s * (1.0f / DM) + 1e-6f);
; #pragma unroll
;     for (int j = 0; j < 4; ++j) {
;         const f32x4 g0 = *((const f32x4*)g + 2 * (lane + 64 * j)), g1 = *((const f32x4*)g + 2 * (lane + 64 * j) + 1);
;         f32x4 o0, o1;
;         o0.x = bflo(v[j].x) * rs * g0.x; o0.y = bfhi(v[j].x) * rs * g0.y; o0.z = bflo(v[j].y) * rs * g0.z; o0.w = bfhi(v[j].y) * rs * g0.w;
;         o1.x = bflo(v[j].z) * rs * g1.x; o1.y = bfhi(v[j].z) * rs * g1.y; o1.z = bflo(v[j].w) * rs * g1.z; o1.w = bfhi(v[j].w) * rs * g1.w;
;         *((f32x4*)orow + 2 * (lane + 64 * j)) = o0; *((f32x4*)orow + 2 * (lane + 64 * j) + 1) = o1;
;     }
; }
.Lp10_nopf:
	v_and_b32_e32 v42, 0xffff0000, v21
	v_lshlrev_b32_e32 v46, 16, v22
	v_and_b32_e32 v47, 0xffff0000, v22
	v_lshlrev_b32_e32 v22, 16, v23
	v_and_b32_e32 v23, 0xffff0000, v23
	v_pk_mul_f32 v[64:65], v[46:47], v[46:47]
	v_pk_mul_f32 v[66:67], v[22:23], v[22:23]
	v_add_f32_e32 v17, v65, v64
	v_lshlrev_b32_e32 v44, 16, v24
	v_and_b32_e32 v45, 0xffff0000, v24
	v_add_f32_e32 v17, v66, v17
	v_lshlrev_b32_e32 v43, 16, v21
	v_lshlrev_b32_e32 v56, 16, v20
	v_and_b32_e32 v57, 0xffff0000, v20
	v_pk_mul_f32 v[20:21], v[44:45], v[44:45]
	v_add_f32_e32 v17, v67, v17
	v_lshlrev_b32_e32 v24, 16, v25
	v_and_b32_e32 v25, 0xffff0000, v25
	v_add_f32_e32 v17, v20, v17
	v_pk_mul_f32 v[62:63], v[24:25], v[24:25]
	v_add_f32_e32 v17, v21, v17
	v_lshlrev_b32_e32 v50, 16, v26
	v_and_b32_e32 v51, 0xffff0000, v26
	v_add_f32_e32 v17, v62, v17
	v_pk_mul_f32 v[72:73], v[50:51], v[50:51]
	v_add_f32_e32 v17, v63, v17
	v_lshlrev_b32_e32 v26, 16, v27
	v_and_b32_e32 v27, 0xffff0000, v27
	v_add_f32_e32 v17, v72, v17
	v_pk_mul_f32 v[74:75], v[26:27], v[26:27]
	v_add_f32_e32 v17, v73, v17
	v_lshlrev_b32_e32 v48, 16, v28
	v_and_b32_e32 v49, 0xffff0000, v28
	v_add_f32_e32 v17, v74, v17
	v_pk_mul_f32 v[68:69], v[48:49], v[48:49]
	v_add_f32_e32 v17, v75, v17
	v_lshlrev_b32_e32 v28, 16, v29
	v_and_b32_e32 v29, 0xffff0000, v29
	v_add_f32_e32 v17, v68, v17
	v_pk_mul_f32 v[70:71], v[28:29], v[28:29]
	v_add_f32_e32 v17, v69, v17
	v_lshlrev_b32_e32 v54, 16, v30
	v_and_b32_e32 v55, 0xffff0000, v30
	v_add_f32_e32 v17, v70, v17
	v_pk_mul_f32 v[80:81], v[54:55], v[54:55]
	v_add_f32_e32 v17, v71, v17
	v_lshlrev_b32_e32 v30, 16, v31
	v_and_b32_e32 v31, 0xffff0000, v31
	v_add_f32_e32 v17, v80, v17
	v_pk_mul_f32 v[82:83], v[30:31], v[30:31]
	v_add_f32_e32 v17, v81, v17
	v_lshlrev_b32_e32 v52, 16, v32
	v_and_b32_e32 v53, 0xffff0000, v32
	v_add_f32_e32 v17, v82, v17
	v_pk_mul_f32 v[76:77], v[52:53], v[52:53]
	v_add_f32_e32 v17, v83, v17
	v_lshlrev_b32_e32 v32, 16, v33
	v_and_b32_e32 v33, 0xffff0000, v33
	v_add_f32_e32 v17, v76, v17
	v_pk_mul_f32 v[78:79], v[32:33], v[32:33]
	v_add_f32_e32 v17, v77, v17
	v_lshlrev_b32_e32 v58, 16, v18
	v_and_b32_e32 v59, 0xffff0000, v18
	v_add_f32_e32 v17, v78, v17
	v_pk_mul_f32 v[86:87], v[58:59], v[58:59]
	v_add_f32_e32 v17, v79, v17
	v_lshlrev_b32_e32 v60, 16, v19
	v_and_b32_e32 v61, 0xffff0000, v19
	v_add_f32_e32 v17, v86, v17
	v_pk_mul_f32 v[88:89], v[60:61], v[60:61]
	v_add_f32_e32 v17, v87, v17
	v_add_f32_e32 v17, v88, v17
	v_pk_mul_f32 v[84:85], v[56:57], v[56:57]
	v_add_f32_e32 v17, v89, v17
	v_add_f32_e32 v17, v84, v17
	v_pk_mul_f32 v[18:19], v[42:43], v[42:43]
	v_add_f32_e32 v17, v85, v17
	v_add_f32_e32 v17, v19, v17
	v_add_f32_e32 v17, v18, v17
	ds_bpermute_b32 v18, v10, v17
	s_waitcnt lgkmcnt(0)
	v_add_f32_e32 v17, v17, v18
	ds_bpermute_b32 v18, v11, v17
	s_waitcnt lgkmcnt(0)
	v_add_f32_e32 v17, v17, v18
	ds_bpermute_b32 v18, v12, v17
	s_waitcnt lgkmcnt(0)
	v_add_f32_e32 v17, v17, v18
	ds_bpermute_b32 v18, v13, v17
	s_waitcnt lgkmcnt(0)
	v_add_f32_e32 v17, v17, v18
	ds_bpermute_b32 v18, v14, v17
	s_waitcnt lgkmcnt(0)
	v_add_f32_e32 v17, v17, v18
	ds_bpermute_b32 v18, v15, v17
	s_waitcnt lgkmcnt(0)
	v_add_f32_e32 v17, v17, v18
	v_fmamk_f32 v17, v17, 0x3a000000, v16
	v_rsq_f32_e32 v62, v17
	s_nop 0
	v_pk_mul_f32 v[18:19], v[62:63], v[46:47] op_sel_hi:[0,1]
	v_pk_mul_f32 v[20:21], v[62:63], v[22:23] op_sel_hi:[0,1]
	v_pk_mul_f32 v[22:23], v[62:63], v[44:45] op_sel_hi:[0,1]
	v_pk_mul_f32 v[24:25], v[62:63], v[24:25] op_sel_hi:[0,1]
	v_pk_mul_f32 v[20:21], v[98:99], v[20:21]
	v_pk_mul_f32 v[18:19], v[96:97], v[18:19]
	v_pk_mul_f32 v[24:25], v[102:103], v[24:25]
	v_pk_mul_f32 v[22:23], v[100:101], v[22:23]
	global_store_dwordx4 v[6:7], v[18:21], off offset:-4096 nt
	global_store_dwordx4 v[6:7], v[22:25], off offset:-4080 nt
	v_pk_mul_f32 v[26:27], v[62:63], v[26:27] op_sel_hi:[0,1]
	v_pk_mul_f32 v[34:35], v[62:63], v[50:51] op_sel_hi:[0,1]
	v_pk_mul_f32 v[28:29], v[62:63], v[28:29] op_sel_hi:[0,1]
	v_pk_mul_f32 v[36:37], v[62:63], v[48:49] op_sel_hi:[0,1]
	v_pk_mul_f32 v[18:19], v[104:105], v[34:35]
	v_pk_mul_f32 v[20:21], v[106:107], v[26:27]
	v_pk_mul_f32 v[22:23], v[108:109], v[36:37]
	v_pk_mul_f32 v[24:25], v[110:111], v[28:29]
	global_store_dwordx4 v[6:7], v[18:21], off offset:-2048 nt
	global_store_dwordx4 v[6:7], v[22:25], off offset:-2032 nt
	v_pk_mul_f32 v[26:27], v[62:63], v[30:31] op_sel_hi:[0,1]
	v_pk_mul_f32 v[28:29], v[62:63], v[54:55] op_sel_hi:[0,1]
	v_pk_mul_f32 v[30:31], v[62:63], v[32:33] op_sel_hi:[0,1]
	v_pk_mul_f32 v[32:33], v[62:63], v[52:53] op_sel_hi:[0,1]
	v_pk_mul_f32 v[18:19], v[112:113], v[28:29]
	v_pk_mul_f32 v[20:21], v[114:115], v[26:27]
	v_pk_mul_f32 v[22:23], v[116:117], v[32:33]
	v_pk_mul_f32 v[24:25], v[118:119], v[30:31]
	global_store_dwordx4 v[6:7], v[18:21], off nt
	global_store_dwordx4 v[6:7], v[22:25], off offset:16 nt
	v_pk_mul_f32 v[26:27], v[62:63], v[60:61] op_sel_hi:[0,1]
	v_pk_mul_f32 v[28:29], v[62:63], v[58:59] op_sel_hi:[0,1]
	v_pk_mul_f32 v[30:31], v[62:63], v[56:57] op_sel_hi:[0,1]
	v_pk_mul_f32 v[32:33], v[62:63], v[42:43] op_sel_hi:[0,1]
	v_pk_mul_f32 v[18:19], v[120:121], v[28:29]
	v_pk_mul_f32 v[20:21], v[122:123], v[26:27]
	v_pk_mul_f32 v[22:23], v[124:125], v[30:31]
	v_pk_mul_f32 v[24:25], v[126:127], v[32:33] op_sel:[0,1] op_sel_hi:[1,0]
	global_store_dwordx4 v[6:7], v[18:21], off offset:2048 nt
	global_store_dwordx4 v[6:7], v[22:25], off offset:2064 nt
	v_lshl_add_u64 v[6:7], v[6:7], 0, s[0:1]
	s_cbranch_scc0 .LBB0_1162
